# first work-queue index of P2/P3 fetched at barrier arrival (alongside the arrival atomic)
# speedup vs baseline: 1.0103x; 1.0103x over previous
; #define LAS __attribute__((address_space(3)))
; __device__ __forceinline__ unsigned xb_add(unsigned* p, unsigned v) { return __hip_atomic_fetch_add(p, v, __ATOMIC_RELAXED, __HIP_MEMORY_SCOPE_AGENT); }
; __device__ __forceinline__ void xcd_barrier(const XcdBarrier& b) {
;     ...
;         if (nloc == 0u) { xcd_barrier_complete(bar, b.x, nloc, nx); b.st[0] = nloc; b.st[1] = nx; }
;         const unsigned old = xb_add(&bar[XB_XSUB(b.x)], 1u);
;         const unsigned gen = old / nloc;
; __global__ void __launch_bounds__(NWAVES * 64, 2) hybrid_fwd(Args args) {
;     ...
;                 unsigned* qc = (unsigned*)(wsl + WS_CTL) + CW_Q + (chunk * 2 + 0) * 64; LAS unsigned* slot = (LAS unsigned*)(lds + LDSCTL_OFF + 64);
;                 for (;;) {
;                     if (threadIdx.x == 0) *slot = __hip_atomic_fetch_add(qc, 1u, __ATOMIC_RELAXED, __HIP_MEMORY_SCOPE_AGENT);
.LBB0_366:
	s_lshl_b32 s2, s2, 8
	s_mov_b64 s[12:13], exec
	s_add_u32 s2, s6, s2
	s_addc_u32 s9, s7, 0
	v_mbcnt_lo_u32_b32 v2, s12, 0
	s_add_u32 s8, s2, 0x4000
	v_mbcnt_hi_u32_b32 v2, s13, v2
	s_addc_u32 s9, s9, 0
	v_cmp_eq_u32_e32 vcc, 0, v2
	s_and_saveexec_b64 s[14:15], vcc
	s_cbranch_execz .LBB0_368
	s_bcnt1_i32_b64 s2, s[12:13]
	v_mov_b32_e32 v4, s2
	v_mov_b32_e32 v5, 0x1000
	global_atomic_add v4, v5, v4, s[8:9] offset:1024 sc0
	s_lshl_b32 s100, s95, 9
	s_add_u32 s100, s36, s100
	s_addc_u32 s101, s37, 0
	s_add_u32 s100, s100, 0xc000
	s_addc_u32 s101, s101, 0
	v_mov_b32_e32 v251, 0
	v_mov_b32_e32 v252, 1
	global_atomic_add v252, v251, v252, s[100:101] sc0

; #define LAS __attribute__((address_space(3)))
; template <class T_> __device__ __forceinline__ T_* as_global(T_* p) { return (T_*)(GAS T_*)p; }
; #define KA() ({ KArgs p_ = (KArgs)__builtin_amdgcn_kernarg_segment_ptr(); asm volatile("" : "+s"(p_)); p_; })
; __global__ void __launch_bounds__(NWAVES * 64, 2) hybrid_fwd(Args args) {
;     ...
;                 KArgs ka = KA(); const LruPtrs lp{as_global(ka->conv_w), as_global(ka->conv_b), as_global(ka->b_lru_r), as_global(ka->b_lru_i), as_global(ka->ws)};
;                 unsigned* qc = (unsigned*)(wsl + WS_CTL) + CW_Q + (chunk * 2 + 0) * 64; LAS unsigned* slot = (LAS unsigned*)(lds + LDSCTL_OFF + 64);
;                 for (;;) {
;                     if (threadIdx.x == 0) *slot = __hip_atomic_fetch_add(qc, 1u, __ATOMIC_RELAXED, __HIP_MEMORY_SCOPE_AGENT);
;                     __syncthreads();
;                     const int L = __builtin_amdgcn_readfirstlane((int)*slot);
.LBB0_402:
	s_or_b64 exec, exec, s[4:5]
	s_mov_b64 s[4:5], s[0:1]
	s_lshl_b32 s2, s95, 24
	s_waitcnt lgkmcnt(0)
	s_barrier
	s_add_u32 s77, s36, 0x3200000
	s_load_dwordx4 s[12:15], s[4:5], 0x20
	s_load_dwordx2 s[6:7], s[4:5], 0x38
	s_load_dwordx2 s[8:9], s[4:5], 0x48
	s_load_dwordx2 s[40:41], s[4:5], 0xa0
	s_addc_u32 s33, s37, 0
	s_lshl_b32 s18, s95, 7
	s_lshl_b64 s[4:5], s[18:19], 2
	v_writelane_b32 v255, s2, 8
	s_add_u32 s2, s36, s4
	s_addc_u32 s4, s37, s5
	s_add_u32 s38, s2, 0xc000
	s_addc_u32 s39, s4, 0
	s_lshl_b32 s25, s95, 5
	s_mov_b32 s99, 1
	s_branch .LBB0_406

; #define LAS __attribute__((address_space(3)))
; __device__ __forceinline__ unsigned xb_add(unsigned* p, unsigned v) { return __hip_atomic_fetch_add(p, v, __ATOMIC_RELAXED, __HIP_MEMORY_SCOPE_AGENT); }
; __device__ __forceinline__ void xcd_barrier(const XcdBarrier& b) {
;     ...
;         if (nloc == 0u) { xcd_barrier_complete(bar, b.x, nloc, nx); b.st[0] = nloc; b.st[1] = nx; }
;         const unsigned old = xb_add(&bar[XB_XSUB(b.x)], 1u);
;         const unsigned gen = old / nloc;
; __global__ void __launch_bounds__(NWAVES * 64, 2) hybrid_fwd(Args args) {
;     ...
;                 unsigned* qc = (unsigned*)(wsl + WS_CTL) + CW_Q + (chunk * 2 + 1) * 64; LAS unsigned* slot = (LAS unsigned*)(lds + LDSCTL_OFF + 64);
;                 for (;;) {
;                     if (threadIdx.x == 0) *slot = __hip_atomic_fetch_add(qc, 1u, __ATOMIC_RELAXED, __HIP_MEMORY_SCOPE_AGENT);
.LBB0_497:
	s_lshl_b32 s2, s2, 8
	s_mov_b64 s[14:15], exec
	s_add_u32 s2, s8, s2
	s_addc_u32 s13, s9, 0
	v_mbcnt_lo_u32_b32 v2, s14, 0
	s_add_u32 s12, s2, 0x4000
	v_mbcnt_hi_u32_b32 v2, s15, v2
	s_addc_u32 s13, s13, 0
	v_cmp_eq_u32_e32 vcc, 0, v2
	s_and_saveexec_b64 s[40:41], vcc
	s_cbranch_execz .LBB0_499
	s_bcnt1_i32_b64 s2, s[14:15]
	v_mov_b32_e32 v4, s2
	v_mov_b32_e32 v5, 0x1000
	global_atomic_add v4, v5, v4, s[12:13] offset:1024 sc0
	v_mov_b32_e32 v251, 0
	v_mov_b32_e32 v252, 1
	global_atomic_add v252, v251, v252, s[38:39] offset:256 sc0

; #define LAS __attribute__((address_space(3)))
; template <class T_> __device__ __forceinline__ T_* as_global(T_* p) { return (T_*)(GAS T_*)p; }
; #define KA() ({ KArgs p_ = (KArgs)__builtin_amdgcn_kernarg_segment_ptr(); asm volatile("" : "+s"(p_)); p_; })
; __global__ void __launch_bounds__(NWAVES * 64, 2) hybrid_fwd(Args args) {
;     ...
;                 KArgs ka = KA(); const LruPtrs lp{as_global(ka->conv_w), as_global(ka->conv_b), as_global(ka->b_lru_r), as_global(ka->b_lru_i), as_global(ka->ws)};
;                 unsigned* qc = (unsigned*)(wsl + WS_CTL) + CW_Q + (chunk * 2 + 1) * 64; LAS unsigned* slot = (LAS unsigned*)(lds + LDSCTL_OFF + 64);
;                 for (;;) {
;                     if (threadIdx.x == 0) *slot = __hip_atomic_fetch_add(qc, 1u, __ATOMIC_RELAXED, __HIP_MEMORY_SCOPE_AGENT);
;                     __syncthreads();
;                     const int L = __builtin_amdgcn_readfirstlane((int)*slot);
.LBB0_533:
	s_or_b64 exec, exec, s[6:7]
	s_add_u32 s54, s36, 0x10000
	s_addc_u32 s55, s37, 0
	s_add_u32 s56, s36, 0x17c00000
	s_addc_u32 s57, s37, 0
	s_add_u32 s58, s36, 0x19c00000
	s_addc_u32 s59, s37, 0
	s_mov_b64 s[6:7], s[0:1]
	s_add_u32 s60, s36, 0x1bc00000
	s_waitcnt lgkmcnt(0)
	s_barrier
	s_load_dwordx2 s[12:13], s[6:7], 0xa0
	s_addc_u32 s61, s37, 0
	s_add_u32 s62, s36, 0x1dc00000
	s_addc_u32 s63, s37, 0
	s_add_u32 s64, s36, 0x32000fc
	s_addc_u32 s65, s37, 0
	s_mov_b32 s99, 1
	s_branch .LBB0_537
